# v20 + uq/ukv: same LDS staging of the ssq block (DMA after the first K-loop barrier, masked ds_read_b128 at the epilogue head)
# speedup vs baseline: 1.0063x; 1.0017x over previous
; #define PG8_STAGE(bufoff, gbase, voff) do { _Pragma("unroll") for (int _i = 0; _i < 2; ++_i) \
;         __builtin_amdgcn_global_load_lds((const unsigned*)((const char*)(gbase) + (voff)[_i]), (LAS unsigned*)(lds + (bufoff) + ldsw + _i * 8192), 16, 0, 0); } while (0)
; #define PG8_LDA(dst, b, h) do { _Pragma("unroll") for (int m = 0; m < 4; ++m) _Pragma("unroll") for (int k = 0; k < 2; ++k) dst[m][k] = *(const LAS bf16x8*)(lds + PG8_SA(b, h) + aoff + m * 2048 + k * 1024); } while (0)
; #define PG8_BAR __builtin_amdgcn_s_barrier()
; template <class Epi>
; __device__ __forceinline__ void gemm_phase(LAS unsigned char* lds, int wave_s, const Gemm g, const StaticOrder S, const Epi E) {
;     ...
;         for (int t = 0; t < nt; t += 2) {
;             const bool last = (t == nt - 2);
;             const char* a1 = cA + (size_t)(t + 1) * kstep;
;             const char* a2 = last ? nA : cA + (size_t)(t + 2) * kstep; const char* b2 = last ? nB : cB + (size_t)(t + 2) * kstep;
;             const char* a3 = a2 + kstep; const char* b3 = b2 + kstep;
;             PG8_LDB(B0, 0, 0); PG8_LDB(B1, 0, 1); PG8_SCHED; PG8_LDA(At, 0, 0); PG8_STAGE(PG8_SA(1, 1), a1 + hstepA, voffA);
;             PG8_WAIT_V(8); PG8_WAIT_L(0); PG8_BAR; PG8_MMA(0, 0, At, B0); PG8_MMA(0, 1, At, B1); PG8_BAR; PG8_SCHED;
;             PG8_LDA(At, 0, 1); PG8_STAGE(PG8_SB(0, 0), b2, voffB); PG8_STAGE(PG8_SB(0, 1), b2 + hstepB, voffB); PG8_STAGE(PG8_SA(0, 0), a2, voffA);
;             PG8_WAIT_V(8); PG8_WAIT_L(0); PG8_BAR; PG8_MMA(1, 0, At, B0); PG8_MMA(1, 1, At, B1); PG8_BAR; PG8_SCHED;
;             PG8_LDB(B0, 1, 0); PG8_LDB(B1, 1, 1); PG8_SCHED; PG8_LDA(At, 1, 0); PG8_STAGE(PG8_SA(0, 1), a2 + hstepA, voffA);
;             PG8_WAIT_V(8); PG8_WAIT_L(0); PG8_BAR; PG8_MMA(0, 0, At, B0); PG8_MMA(0, 1, At, B1); PG8_BAR; PG8_SCHED;
;             PG8_LDA(At, 1, 1); PG8_STAGE(PG8_SB(1, 0), b3, voffB); PG8_STAGE(PG8_SB(1, 1), b3 + hstepB, voffB); PG8_STAGE(PG8_SA(1, 0), a3, voffA);
;             PG8_WAIT_V(8); PG8_WAIT_L(0); PG8_BAR; PG8_MMA(1, 0, At, B0); PG8_MMA(1, 1, At, B1); PG8_BAR; PG8_SCHED;
; __global__ void __launch_bounds__(512) fwd_megakernel(Args a) {
;     ...
;             { pg8::Gemm g{ACT + C_CQ, Wb + W_UQ, MC, QAW, 384, INP}; pg8::StaticOrder S; S.init(MC, QAW, G, bx);
;               pg8::EpiGen E{QA, QAW, PQ, 1.f / 384.f, 2, nullptr, nullptr, rope, 16, 3}; pg8::gemm_phase(lds, wave_s, g, S, E); }
.LBB0_565:
	s_add_u32 s20, s18, 0x100
	s_addc_u32 s21, s19, 0
	s_add_i32 s6, 0, 0x10000
	s_cmp_eq_u32 s50, 2
	s_cselect_b32 s25, s1, s21
	s_cselect_b32 s24, s0, s20
	v_add_u32_e32 v0, s6, v166
	s_cselect_b32 s23, s17, s11
	s_cselect_b32 s22, s16, s10
	s_add_i32 s42, 0, 0x14000
	ds_read_b128 v[130:133], v0
	ds_read_b128 v[154:157], v0 offset:1024
	ds_read_b128 v[158:161], v0 offset:2048
	ds_read_b128 v[162:165], v0 offset:3072
	v_add_u32_e32 v0, s42, v166
	ds_read_b128 v[168:171], v0
	ds_read_b128 v[172:175], v0 offset:1024
	ds_read_b128 v[176:179], v0 offset:2048
	ds_read_b128 v[180:183], v0 offset:3072
	v_lshl_add_u64 v[134:135], s[18:19], 0, v[150:151]
	s_add_i32 m0, s27, 0xc000
	ds_read_b128 v[184:187], v167
	ds_read_b128 v[188:191], v167 offset:1024
	ds_read_b128 v[192:195], v167 offset:2048
	ds_read_b128 v[206:209], v167 offset:3072
	ds_read_b128 v[210:213], v167 offset:4096
	ds_read_b128 v[214:217], v167 offset:5120
	ds_read_b128 v[218:221], v167 offset:6144
	ds_read_b128 v[222:225], v167 offset:7168
	global_load_lds_dwordx4 v[134:135], off
	v_lshl_add_u64 v[134:135], s[18:19], 0, v[152:153]
	s_add_i32 m0, s27, 0xe000
	s_nop 0
	global_load_lds_dwordx4 v[134:135], off
	s_waitcnt vmcnt(8)
	s_waitcnt lgkmcnt(0)
	s_barrier
	s_cmp_eq_i32 s50, -2
	s_cbranch_scc0 .Lsq_uq_skip
	v_readlane_b32 s100, v146, 0
	v_readlane_b32 s101, v147, 0
	s_lshl_b32 s98, s40, 14
	s_lshl_b32 s99, s92, 5
	s_add_u32 s98, s98, s99
	s_add_u32 s100, s100, s98
	s_addc_u32 s101, s101, 0
	s_add_i32 m0, s99, 0x24000
	v_lshlrev_b32_e32 v243, 4, v241
	s_nop 1
	global_load_lds_dwordx4 v243, s[100:101]
	global_load_lds_dwordx4 v243, s[100:101] offset:1024
.Lsq_uq_skip:
	s_setprio 1
	s_waitcnt lgkmcnt(0)
	v_mfma_f32_16x16x32_bf16 v[126:129], v[130:133], v[184:187], v[126:129]
	v_mfma_f32_16x16x32_bf16 v[122:125], v[158:161], v[184:187], v[122:125]
	v_mfma_f32_16x16x32_bf16 v[118:121], v[130:133], v[192:195], v[118:121]
	v_mfma_f32_16x16x32_bf16 v[114:117], v[158:161], v[192:195], v[114:117]
	v_mfma_f32_16x16x32_bf16 v[110:113], v[130:133], v[210:213], v[110:113]
	v_mfma_f32_16x16x32_bf16 v[106:109], v[158:161], v[210:213], v[106:109]
	v_mfma_f32_16x16x32_bf16 v[102:105], v[130:133], v[218:221], v[102:105]
	v_mfma_f32_16x16x32_bf16 v[98:101], v[158:161], v[218:221], v[98:101]
	v_mfma_f32_16x16x32_bf16 v[126:129], v[154:157], v[188:191], v[126:129]
	v_mfma_f32_16x16x32_bf16 v[122:125], v[162:165], v[188:191], v[122:125]
	v_mfma_f32_16x16x32_bf16 v[118:121], v[154:157], v[206:209], v[118:121]
	v_mfma_f32_16x16x32_bf16 v[114:117], v[162:165], v[206:209], v[114:117]
	v_mfma_f32_16x16x32_bf16 v[110:113], v[154:157], v[214:217], v[110:113]
	v_mfma_f32_16x16x32_bf16 v[106:109], v[162:165], v[214:217], v[106:109]
	v_mfma_f32_16x16x32_bf16 v[102:105], v[154:157], v[222:225], v[102:105]
	v_mfma_f32_16x16x32_bf16 v[98:101], v[162:165], v[222:225], v[98:101]
	s_setprio 0
	s_setprio 1
	v_mfma_f32_16x16x32_bf16 v[62:65], v[168:171], v[184:187], v[62:65]
	v_mfma_f32_16x16x32_bf16 v[58:61], v[176:179], v[184:187], v[58:61]
	v_mfma_f32_16x16x32_bf16 v[54:57], v[168:171], v[192:195], v[54:57]
	v_mfma_f32_16x16x32_bf16 v[50:53], v[176:179], v[192:195], v[50:53]
	v_mfma_f32_16x16x32_bf16 v[46:49], v[168:171], v[210:213], v[46:49]
	v_mfma_f32_16x16x32_bf16 v[42:45], v[176:179], v[210:213], v[42:45]
	v_mfma_f32_16x16x32_bf16 v[38:41], v[168:171], v[218:221], v[38:41]
	v_mfma_f32_16x16x32_bf16 v[34:37], v[176:179], v[218:221], v[34:37]
	v_mfma_f32_16x16x32_bf16 v[62:65], v[172:175], v[188:191], v[62:65]
	v_mfma_f32_16x16x32_bf16 v[58:61], v[180:183], v[188:191], v[58:61]
	v_mfma_f32_16x16x32_bf16 v[54:57], v[172:175], v[206:209], v[54:57]
	v_mfma_f32_16x16x32_bf16 v[50:53], v[180:183], v[206:209], v[50:53]
	v_mfma_f32_16x16x32_bf16 v[46:49], v[172:175], v[214:217], v[46:49]
	v_mfma_f32_16x16x32_bf16 v[42:45], v[180:183], v[214:217], v[42:45]
	v_mfma_f32_16x16x32_bf16 v[38:41], v[172:175], v[222:225], v[38:41]
	v_mfma_f32_16x16x32_bf16 v[34:37], v[180:183], v[222:225], v[34:37]
	s_setprio 0
	s_barrier
	s_add_i32 s6, s6, s26
	v_lshl_add_u64 v[134:135], s[22:23], 0, v[140:141]
	s_mov_b32 m0, s6
	ds_read_b128 v[184:187], v167 offset:16384
	ds_read_b128 v[188:191], v167 offset:17408
	ds_read_b128 v[192:195], v167 offset:18432
	ds_read_b128 v[206:209], v167 offset:19456
	ds_read_b128 v[210:213], v167 offset:20480
	ds_read_b128 v[214:217], v167 offset:21504
	ds_read_b128 v[218:221], v167 offset:22528
	ds_read_b128 v[222:225], v167 offset:23552
	global_load_lds_dwordx4 v[134:135], off
	s_add_i32 m0, s6, 0x2000
	s_add_u32 s6, s22, 0x18000
	v_lshl_add_u64 v[196:197], s[22:23], 0, v[136:137]
	s_addc_u32 s7, s23, 0
	s_add_i32 s18, s42, s26
	global_load_lds_dwordx4 v[196:197], off
	v_lshl_add_u64 v[198:199], s[6:7], 0, v[140:141]
	s_mov_b32 m0, s18
	v_lshl_add_u64 v[200:201], s[24:25], 0, v[138:139]
	global_load_lds_dwordx4 v[198:199], off
	v_lshl_add_u64 v[198:199], s[6:7], 0, v[136:137]
	s_add_i32 m0, s18, 0x2000
	s_nop 0
	global_load_lds_dwordx4 v[198:199], off
	v_lshl_add_u64 v[198:199], s[24:25], 0, v[142:143]
	s_mov_b32 m0, s27
	s_nop 0
	global_load_lds_dwordx4 v[198:199], off
	s_mov_b32 m0, s28
	s_nop 0
	global_load_lds_dwordx4 v[200:201], off
	s_waitcnt vmcnt(8)
	s_waitcnt lgkmcnt(0)
	s_barrier
; #define PG8_STAGE(bufoff, gbase, voff) do { _Pragma("unroll") for (int _i = 0; _i < 2; ++_i) \
;         __builtin_amdgcn_global_load_lds((const unsigned*)((const char*)(gbase) + (voff)[_i]), (LAS unsigned*)(lds + (bufoff) + ldsw + _i * 8192), 16, 0, 0); } while (0)
; #define PG8_LDA(dst, b, h) do { _Pragma("unroll") for (int m = 0; m < 4; ++m) _Pragma("unroll") for (int k = 0; k < 2; ++k) dst[m][k] = *(const LAS bf16x8*)(lds + PG8_SA(b, h) + aoff + m * 2048 + k * 1024); } while (0)
; #define PG8_LDB(dst, b, h) do { _Pragma("unroll") for (int n = 0; n < 2; ++n) _Pragma("unroll") for (int k = 0; k < 2; ++k) dst[n][k] = *(const LAS bf16x8*)(lds + PG8_SB(b, h) + boff + n * 2048 + k * 1024); } while (0)
; #define PG8_MMA(ai, bj, At, Bt) do { __builtin_amdgcn_s_setprio(1); _Pragma("unroll") for (int m = 0; m < 4; ++m) _Pragma("unroll") for (int n = 0; n < 2; ++n) _Pragma("unroll") for (int k = 0; k < 2; ++k) \
;         acc[ai][bj][m][n] = __builtin_amdgcn_mfma_f32_16x16x32_bf16(Bt[n][k], At[m][k], acc[ai][bj][m][n], 0, 0, 0); __builtin_amdgcn_s_setprio(0); } while (0)
; #define PG8_WAIT_V(n) asm volatile("s_waitcnt vmcnt(" #n ")" ::: "memory")
; #define PG8_WAIT_L(n) asm volatile("s_waitcnt lgkmcnt(" #n ")" ::: "memory")
; #define PG8_BAR __builtin_amdgcn_s_barrier()
; #define PG8_SCHED __builtin_amdgcn_sched_barrier(0)
; template <class Epi>
; __device__ __forceinline__ void gemm_phase(LAS unsigned char* lds, int wave_s, const Gemm g, const StaticOrder S, const Epi E) {
;     ...
;             PG8_WAIT_V(8); PG8_WAIT_L(0); PG8_BAR; PG8_MMA(0, 0, At, B0); PG8_MMA(0, 1, At, B1); PG8_BAR; PG8_SCHED;
;             PG8_LDA(At, 0, 1); PG8_STAGE(PG8_SB(0, 0), b2, voffB); PG8_STAGE(PG8_SB(0, 1), b2 + hstepB, voffB); PG8_STAGE(PG8_SA(0, 0), a2, voffA);
;             PG8_WAIT_V(8); PG8_WAIT_L(0); PG8_BAR; PG8_MMA(1, 0, At, B0); PG8_MMA(1, 1, At, B1); PG8_BAR; PG8_SCHED;
;             PG8_LDB(B0, 1, 0); PG8_LDB(B1, 1, 1); PG8_SCHED; PG8_LDA(At, 1, 0); PG8_STAGE(PG8_SA(0, 1), a2 + hstepA, voffA);
;             PG8_WAIT_V(8); PG8_WAIT_L(0); PG8_BAR; PG8_MMA(0, 0, At, B0); PG8_MMA(0, 1, At, B1); PG8_BAR; PG8_SCHED;
	s_setprio 1
	s_waitcnt lgkmcnt(0)
	v_mfma_f32_16x16x32_bf16 v[94:97], v[130:133], v[184:187], v[94:97]
	v_mfma_f32_16x16x32_bf16 v[90:93], v[158:161], v[184:187], v[90:93]
	v_mfma_f32_16x16x32_bf16 v[86:89], v[130:133], v[192:195], v[86:89]
	v_mfma_f32_16x16x32_bf16 v[82:85], v[158:161], v[192:195], v[82:85]
	v_mfma_f32_16x16x32_bf16 v[78:81], v[130:133], v[210:213], v[78:81]
	v_mfma_f32_16x16x32_bf16 v[74:77], v[158:161], v[210:213], v[74:77]
	v_mfma_f32_16x16x32_bf16 v[70:73], v[130:133], v[218:221], v[70:73]
	v_mfma_f32_16x16x32_bf16 v[66:69], v[158:161], v[218:221], v[66:69]
	v_mfma_f32_16x16x32_bf16 v[94:97], v[154:157], v[188:191], v[94:97]
	v_mfma_f32_16x16x32_bf16 v[90:93], v[162:165], v[188:191], v[90:93]
	v_mfma_f32_16x16x32_bf16 v[86:89], v[154:157], v[206:209], v[86:89]
	v_mfma_f32_16x16x32_bf16 v[82:85], v[162:165], v[206:209], v[82:85]
	v_mfma_f32_16x16x32_bf16 v[78:81], v[154:157], v[214:217], v[78:81]
	v_mfma_f32_16x16x32_bf16 v[74:77], v[162:165], v[214:217], v[74:77]
	v_mfma_f32_16x16x32_bf16 v[70:73], v[154:157], v[222:225], v[70:73]
	v_mfma_f32_16x16x32_bf16 v[66:69], v[162:165], v[222:225], v[66:69]
	s_setprio 0
	s_setprio 1
	v_mfma_f32_16x16x32_bf16 v[30:33], v[168:171], v[184:187], v[30:33]
	v_mfma_f32_16x16x32_bf16 v[26:29], v[176:179], v[184:187], v[26:29]
	v_mfma_f32_16x16x32_bf16 v[22:25], v[168:171], v[192:195], v[22:25]
	v_mfma_f32_16x16x32_bf16 v[18:21], v[176:179], v[192:195], v[18:21]
	v_mfma_f32_16x16x32_bf16 v[14:17], v[168:171], v[210:213], v[14:17]
	v_mfma_f32_16x16x32_bf16 v[10:13], v[176:179], v[210:213], v[10:13]
	v_mfma_f32_16x16x32_bf16 v[6:9], v[168:171], v[218:221], v[6:9]
	v_mfma_f32_16x16x32_bf16 v[2:5], v[176:179], v[218:221], v[2:5]
	v_mfma_f32_16x16x32_bf16 v[30:33], v[172:175], v[188:191], v[30:33]
	v_mfma_f32_16x16x32_bf16 v[26:29], v[180:183], v[188:191], v[26:29]
	v_mfma_f32_16x16x32_bf16 v[22:25], v[172:175], v[206:209], v[22:25]
	v_mfma_f32_16x16x32_bf16 v[18:21], v[180:183], v[206:209], v[18:21]
	v_mfma_f32_16x16x32_bf16 v[14:17], v[172:175], v[214:217], v[14:17]
	v_mfma_f32_16x16x32_bf16 v[10:13], v[180:183], v[214:217], v[10:13]
	v_mfma_f32_16x16x32_bf16 v[6:9], v[172:175], v[222:225], v[6:9]
	v_mfma_f32_16x16x32_bf16 v[2:5], v[180:183], v[222:225], v[2:5]
	s_setprio 0
	s_barrier
	s_add_i32 s18, 0, 0x18000
	v_add_u32_e32 v0, s18, v166
	s_add_i32 s19, 0, 0x1c000
	ds_read_b128 v[130:133], v0
	ds_read_b128 v[154:157], v0 offset:1024
	ds_read_b128 v[158:161], v0 offset:2048
	ds_read_b128 v[162:165], v0 offset:3072
	v_add_u32_e32 v0, s19, v166
	ds_read_b128 v[168:171], v0
	ds_read_b128 v[172:175], v0 offset:1024
	ds_read_b128 v[176:179], v0 offset:2048
	ds_read_b128 v[180:183], v0 offset:3072
	s_add_u32 s6, s24, 0x210000
	s_addc_u32 s7, s25, 0
	s_mov_b32 m0, s29
	v_lshl_add_u64 v[202:203], s[6:7], 0, v[142:143]
	ds_read_b128 v[184:187], v167 offset:32768
	ds_read_b128 v[188:191], v167 offset:33792
	ds_read_b128 v[192:195], v167 offset:34816
	ds_read_b128 v[206:209], v167 offset:35840
	ds_read_b128 v[210:213], v167 offset:36864
	ds_read_b128 v[214:217], v167 offset:37888
	ds_read_b128 v[218:221], v167 offset:38912
	ds_read_b128 v[222:225], v167 offset:39936
	global_load_lds_dwordx4 v[202:203], off
	v_lshl_add_u64 v[202:203], s[6:7], 0, v[138:139]
	s_mov_b32 m0, s30
	s_nop 0
	global_load_lds_dwordx4 v[202:203], off
	s_waitcnt vmcnt(8)
	s_waitcnt lgkmcnt(0)
	s_barrier
	s_setprio 1
	s_waitcnt lgkmcnt(0)
	v_mfma_f32_16x16x32_bf16 v[126:129], v[130:133], v[184:187], v[126:129]
	v_mfma_f32_16x16x32_bf16 v[122:125], v[158:161], v[184:187], v[122:125]
	v_mfma_f32_16x16x32_bf16 v[118:121], v[130:133], v[192:195], v[118:121]
	v_mfma_f32_16x16x32_bf16 v[114:117], v[158:161], v[192:195], v[114:117]
	v_mfma_f32_16x16x32_bf16 v[110:113], v[130:133], v[210:213], v[110:113]
	v_mfma_f32_16x16x32_bf16 v[106:109], v[158:161], v[210:213], v[106:109]
	v_mfma_f32_16x16x32_bf16 v[102:105], v[130:133], v[218:221], v[102:105]
	v_mfma_f32_16x16x32_bf16 v[98:101], v[158:161], v[218:221], v[98:101]
	v_mfma_f32_16x16x32_bf16 v[126:129], v[154:157], v[188:191], v[126:129]
	v_mfma_f32_16x16x32_bf16 v[122:125], v[162:165], v[188:191], v[122:125]
	v_mfma_f32_16x16x32_bf16 v[118:121], v[154:157], v[206:209], v[118:121]
	v_mfma_f32_16x16x32_bf16 v[114:117], v[162:165], v[206:209], v[114:117]
	v_mfma_f32_16x16x32_bf16 v[110:113], v[154:157], v[214:217], v[110:113]
	v_mfma_f32_16x16x32_bf16 v[106:109], v[162:165], v[214:217], v[106:109]
	v_mfma_f32_16x16x32_bf16 v[102:105], v[154:157], v[222:225], v[102:105]
	v_mfma_f32_16x16x32_bf16 v[98:101], v[162:165], v[222:225], v[98:101]
	s_setprio 0
	s_setprio 1
	v_mfma_f32_16x16x32_bf16 v[62:65], v[168:171], v[184:187], v[62:65]
	v_mfma_f32_16x16x32_bf16 v[58:61], v[176:179], v[184:187], v[58:61]
	v_mfma_f32_16x16x32_bf16 v[54:57], v[168:171], v[192:195], v[54:57]
	v_mfma_f32_16x16x32_bf16 v[50:53], v[176:179], v[192:195], v[50:53]
	v_mfma_f32_16x16x32_bf16 v[46:49], v[168:171], v[210:213], v[46:49]
	v_mfma_f32_16x16x32_bf16 v[42:45], v[176:179], v[210:213], v[42:45]
	v_mfma_f32_16x16x32_bf16 v[38:41], v[168:171], v[218:221], v[38:41]
	v_mfma_f32_16x16x32_bf16 v[34:37], v[176:179], v[218:221], v[34:37]
	v_mfma_f32_16x16x32_bf16 v[62:65], v[172:175], v[188:191], v[62:65]
	v_mfma_f32_16x16x32_bf16 v[58:61], v[180:183], v[188:191], v[58:61]
	v_mfma_f32_16x16x32_bf16 v[54:57], v[172:175], v[206:209], v[54:57]
	v_mfma_f32_16x16x32_bf16 v[50:53], v[180:183], v[206:209], v[50:53]
	v_mfma_f32_16x16x32_bf16 v[46:49], v[172:175], v[214:217], v[46:49]
	v_mfma_f32_16x16x32_bf16 v[42:45], v[180:183], v[214:217], v[42:45]
	v_mfma_f32_16x16x32_bf16 v[38:41], v[172:175], v[222:225], v[38:41]
	v_mfma_f32_16x16x32_bf16 v[34:37], v[180:183], v[222:225], v[34:37]
	s_setprio 0
	s_barrier
; #define PG8_STAGE(bufoff, gbase, voff) do { _Pragma("unroll") for (int _i = 0; _i < 2; ++_i) \
;         __builtin_amdgcn_global_load_lds((const unsigned*)((const char*)(gbase) + (voff)[_i]), (LAS unsigned*)(lds + (bufoff) + ldsw + _i * 8192), 16, 0, 0); } while (0)
; #define PG8_LDA(dst, b, h) do { _Pragma("unroll") for (int m = 0; m < 4; ++m) _Pragma("unroll") for (int k = 0; k < 2; ++k) dst[m][k] = *(const LAS bf16x8*)(lds + PG8_SA(b, h) + aoff + m * 2048 + k * 1024); } while (0)
; #define PG8_MMA(ai, bj, At, Bt) do { __builtin_amdgcn_s_setprio(1); _Pragma("unroll") for (int m = 0; m < 4; ++m) _Pragma("unroll") for (int n = 0; n < 2; ++n) _Pragma("unroll") for (int k = 0; k < 2; ++k) \
;         acc[ai][bj][m][n] = __builtin_amdgcn_mfma_f32_16x16x32_bf16(Bt[n][k], At[m][k], acc[ai][bj][m][n], 0, 0, 0); __builtin_amdgcn_s_setprio(0); } while (0)
; #define PG8_WAIT_V(n) asm volatile("s_waitcnt vmcnt(" #n ")" ::: "memory")
; #define PG8_WAIT_L(n) asm volatile("s_waitcnt lgkmcnt(" #n ")" ::: "memory")
; #define PG8_BAR __builtin_amdgcn_s_barrier()
; #define PG8_SCHED __builtin_amdgcn_sched_barrier(0)
; __device__ __forceinline__ float row_ssq(const float* part, int pitch, int n4, int row, int fq) {
;     f32x4 v = (f32x4){0.f, 0.f, 0.f, 0.f};
;     if (fq < n4) v = *(const f32x4*)(part + (size_t)row * pitch + 4 * fq);
; template <class Epi>
; __device__ __forceinline__ void gemm_phase(LAS unsigned char* lds, int wave_s, const Gemm g, const StaticOrder S, const Epi E) {
;     ...
;             PG8_WAIT_V(8); PG8_WAIT_L(0); PG8_BAR; PG8_MMA(0, 0, At, B0); PG8_MMA(0, 1, At, B1); PG8_BAR; PG8_SCHED;
;             PG8_LDA(At, 1, 1); PG8_STAGE(PG8_SB(1, 0), b3, voffB); PG8_STAGE(PG8_SB(1, 1), b3 + hstepB, voffB); PG8_STAGE(PG8_SA(1, 0), a3, voffA);
;             PG8_WAIT_V(8); PG8_WAIT_L(0); PG8_BAR; PG8_MMA(1, 0, At, B0); PG8_MMA(1, 1, At, B1); PG8_BAR; PG8_SCHED;
;         }
;         if (wr == 0) PG8_BAR;
;         E(acc, cur, wr, wc, fr, fq);
;     __device__ __forceinline__ void operator()(const f32x4 (&acc)[2][2][4][2], const Unit& u, int wr, int wc, int fr, int fq) const {
;     ...
;             for (int m = 0; m < 4; ++m) rsv[ai][m] = ssq_in ? rsqrtf(row_ssq(ssq_in, in_pitch, in_n4, row0 + ai * HALF + m * 16, fq) * inv_k + EPS) : 1.f;
	s_add_i32 s6, s18, s26
	v_lshl_add_u64 v[134:135], v[134:135], 0, s[8:9]
	s_mov_b32 m0, s6
	ds_read_b128 v[184:187], v167 offset:49152
	ds_read_b128 v[188:191], v167 offset:50176
	ds_read_b128 v[192:195], v167 offset:51200
	ds_read_b128 v[206:209], v167 offset:52224
	ds_read_b128 v[210:213], v167 offset:53248
	ds_read_b128 v[214:217], v167 offset:54272
	ds_read_b128 v[218:221], v167 offset:55296
	ds_read_b128 v[222:225], v167 offset:56320
	global_load_lds_dwordx4 v[134:135], off
	s_add_i32 m0, s6, 0x2000
	s_add_u32 s6, s22, 0x18080
	v_lshl_add_u64 v[134:135], v[196:197], 0, s[8:9]
	s_addc_u32 s7, s23, 0
	s_add_i32 s18, s19, s26
	global_load_lds_dwordx4 v[134:135], off
	v_lshl_add_u64 v[134:135], s[6:7], 0, v[140:141]
	s_mov_b32 m0, s18
	s_nop 0
	global_load_lds_dwordx4 v[134:135], off
	v_lshl_add_u64 v[134:135], s[6:7], 0, v[136:137]
	s_add_i32 m0, s18, 0x2000
	s_nop 0
	global_load_lds_dwordx4 v[134:135], off
	v_lshl_add_u64 v[134:135], v[198:199], 0, s[8:9]
	s_mov_b32 m0, s34
	s_nop 0
	global_load_lds_dwordx4 v[134:135], off
	v_lshl_add_u64 v[134:135], v[200:201], 0, s[8:9]
	s_mov_b32 m0, s35
	s_nop 0
	global_load_lds_dwordx4 v[134:135], off
	s_waitcnt vmcnt(8)
	s_waitcnt lgkmcnt(0)
	s_barrier
	s_setprio 1
	s_waitcnt lgkmcnt(0)
	v_mfma_f32_16x16x32_bf16 v[94:97], v[130:133], v[184:187], v[94:97]
	v_mfma_f32_16x16x32_bf16 v[90:93], v[158:161], v[184:187], v[90:93]
	v_mfma_f32_16x16x32_bf16 v[86:89], v[130:133], v[192:195], v[86:89]
	v_mfma_f32_16x16x32_bf16 v[82:85], v[158:161], v[192:195], v[82:85]
	v_mfma_f32_16x16x32_bf16 v[78:81], v[130:133], v[210:213], v[78:81]
	v_mfma_f32_16x16x32_bf16 v[74:77], v[158:161], v[210:213], v[74:77]
	v_mfma_f32_16x16x32_bf16 v[70:73], v[130:133], v[218:221], v[70:73]
	v_mfma_f32_16x16x32_bf16 v[66:69], v[158:161], v[218:221], v[66:69]
	v_mfma_f32_16x16x32_bf16 v[94:97], v[154:157], v[188:191], v[94:97]
	v_mfma_f32_16x16x32_bf16 v[90:93], v[162:165], v[188:191], v[90:93]
	v_mfma_f32_16x16x32_bf16 v[86:89], v[154:157], v[206:209], v[86:89]
	v_mfma_f32_16x16x32_bf16 v[82:85], v[162:165], v[206:209], v[82:85]
	v_mfma_f32_16x16x32_bf16 v[78:81], v[154:157], v[214:217], v[78:81]
	v_mfma_f32_16x16x32_bf16 v[74:77], v[162:165], v[214:217], v[74:77]
	v_mfma_f32_16x16x32_bf16 v[70:73], v[154:157], v[222:225], v[70:73]
	v_mfma_f32_16x16x32_bf16 v[66:69], v[162:165], v[222:225], v[66:69]
	s_setprio 0
	s_setprio 1
	v_mfma_f32_16x16x32_bf16 v[30:33], v[168:171], v[184:187], v[30:33]
	v_mfma_f32_16x16x32_bf16 v[26:29], v[176:179], v[184:187], v[26:29]
	v_mfma_f32_16x16x32_bf16 v[22:25], v[168:171], v[192:195], v[22:25]
	v_mfma_f32_16x16x32_bf16 v[18:21], v[176:179], v[192:195], v[18:21]
	v_mfma_f32_16x16x32_bf16 v[14:17], v[168:171], v[210:213], v[14:17]
	v_mfma_f32_16x16x32_bf16 v[10:13], v[176:179], v[210:213], v[10:13]
	v_mfma_f32_16x16x32_bf16 v[6:9], v[168:171], v[218:221], v[6:9]
	v_mfma_f32_16x16x32_bf16 v[2:5], v[176:179], v[218:221], v[2:5]
	v_mfma_f32_16x16x32_bf16 v[30:33], v[172:175], v[188:191], v[30:33]
	v_mfma_f32_16x16x32_bf16 v[26:29], v[180:183], v[188:191], v[26:29]
	v_mfma_f32_16x16x32_bf16 v[22:25], v[172:175], v[206:209], v[22:25]
	v_mfma_f32_16x16x32_bf16 v[18:21], v[180:183], v[206:209], v[18:21]
	v_mfma_f32_16x16x32_bf16 v[14:17], v[172:175], v[214:217], v[14:17]
	v_mfma_f32_16x16x32_bf16 v[10:13], v[180:183], v[214:217], v[10:13]
	v_mfma_f32_16x16x32_bf16 v[6:9], v[172:175], v[222:225], v[6:9]
	v_mfma_f32_16x16x32_bf16 v[2:5], v[180:183], v[222:225], v[2:5]
	s_setprio 0
	s_barrier
	s_add_i32 s50, s50, 2
	s_add_u32 s10, s10, 0x100
	s_addc_u32 s11, s11, 0
	s_cmp_gt_u32 s50, 3
	s_mov_b64 s[18:19], s[20:21]
	s_cbranch_scc0 .LBB0_565
	s_and_b64 vcc, exec, s[14:15]
	s_cbranch_vccz .LBB0_568
	s_barrier
.LBB0_568:
	v_lshl_add_u32 v154, s40, 8, v145
	v_mov_b32_e32 v130, 0
	v_ashrrev_i32_e32 v155, 31, v154
	s_and_saveexec_b64 s[98:99], s[44:45]
	v_and_b32_e32 v234, 48, v241
	v_lshl_add_u32 v234, v145, 6, v234
	v_add_u32_e32 v234, 0x24000, v234
	ds_read_b128 v[194:197], v234
	ds_read_b128 v[198:201], v234 offset:1024
	ds_read_b128 v[206:209], v234 offset:2048
	ds_read_b128 v[210:213], v234 offset:3072
	ds_read_b128 v[214:217], v234 offset:8192
	ds_read_b128 v[218:221], v234 offset:9216
	ds_read_b128 v[226:229], v234 offset:10240
	ds_read_b128 v[230:233], v234 offset:11264
	s_or_b64 exec, exec, s[98:99]
	v_mov_b32_e32 v132, 0
	v_mov_b32_e32 v156, 0
	v_mov_b32_e32 v157, 0
	v_mov_b32_e32 v133, 0
	s_and_saveexec_b64 s[18:19], s[44:45]
	s_cbranch_execz .LBB0_570
	v_lshlrev_b64 v[132:133], 6, v[154:155]
	v_lshl_add_u64 v[132:133], v[146:147], 0, v[132:133]
	s_waitcnt lgkmcnt(1)
	v_mov_b32_e32 v132, v194
	v_mov_b32_e32 v133, v195
	v_mov_b32_e32 v134, v196
	v_mov_b32_e32 v135, v197
	v_mov_b32_e32 v156, v133
	v_mov_b32_e32 v157, v134
	v_mov_b32_e32 v133, v135
; __device__ __forceinline__ float row_ssq(const float* part, int pitch, int n4, int row, int fq) {
;     f32x4 v = (f32x4){0.f, 0.f, 0.f, 0.f};
;     if (fq < n4) v = *(const f32x4*)(part + (size_t)row * pitch + 4 * fq);
;     float s = (v[0] + v[1]) + (v[2] + v[3]);
;     s += __shfl_xor(s, 16); s += __shfl_xor(s, 32);
;     return s;
; }
;     __device__ __forceinline__ void operator()(const f32x4 (&acc)[2][2][4][2], const Unit& u, int wr, int wc, int fr, int fq) const {
;     ...
;             for (int m = 0; m < 4; ++m) rsv[ai][m] = ssq_in ? rsqrtf(row_ssq(ssq_in, in_pitch, in_n4, row0 + ai * HALF + m * 16, fq) * inv_k + EPS) : 1.f;
.LBB0_570:
	s_or_b64 exec, exec, s[18:19]
	v_pk_add_f32 v[132:133], v[156:157], v[132:133]
	v_xor_b32_e32 v131, 16, v241
	v_add_f32_e32 v0, v132, v133
	v_and_b32_e32 v132, 64, v241
	v_add_u32_e32 v132, 64, v132
	v_cmp_lt_i32_e32 vcc, v131, v132
	v_or_b32_e32 v162, 16, v154
	v_mov_b32_e32 v134, 0
	v_cndmask_b32_e32 v131, v241, v131, vcc
	v_lshlrev_b32_e32 v176, 2, v131
	ds_bpermute_b32 v131, v176, v0
	v_mov_b32_e32 v135, 0
	s_waitcnt lgkmcnt(0)
	v_add_f32_e32 v177, v0, v131
	v_xor_b32_e32 v0, 32, v241
	v_cmp_lt_i32_e32 vcc, v0, v132
	v_mov_b32_e32 v131, 0
	s_nop 0
	v_cndmask_b32_e32 v0, v241, v0, vcc
	v_lshlrev_b32_e32 v168, 2, v0
	ds_bpermute_b32 v178, v168, v177
	s_and_saveexec_b64 s[18:19], s[44:45]
	s_cbranch_execz .LBB0_572
	v_ashrrev_i32_e32 v163, 31, v162
	v_lshlrev_b64 v[130:131], 6, v[162:163]
	v_lshl_add_u64 v[130:131], v[146:147], 0, v[130:131]
	s_waitcnt lgkmcnt(1)
	v_mov_b32_e32 v130, v198
	v_mov_b32_e32 v131, v199
	v_mov_b32_e32 v132, v200
	v_mov_b32_e32 v133, v201
	v_mov_b32_e32 v134, v131
	v_mov_b32_e32 v135, v132
	v_mov_b32_e32 v131, v133
.LBB0_572:
	s_or_b64 exec, exec, s[18:19]
	v_pk_add_f32 v[130:131], v[134:135], v[130:131]
	v_or_b32_e32 v160, 32, v154
	v_add_f32_e32 v0, v130, v131
	ds_bpermute_b32 v131, v176, v0
	v_mov_b32_e32 v130, 0
	v_mov_b32_e32 v132, 0
	v_mov_b32_e32 v156, 0
	v_mov_b32_e32 v157, 0
	s_waitcnt lgkmcnt(0)
	v_add_f32_e32 v0, v0, v131
	ds_bpermute_b32 v175, v168, v0
	v_mov_b32_e32 v133, 0
	s_and_saveexec_b64 s[18:19], s[44:45]
	s_cbranch_execz .LBB0_574
	v_ashrrev_i32_e32 v161, 31, v160
	v_lshlrev_b64 v[132:133], 6, v[160:161]
	v_lshl_add_u64 v[132:133], v[146:147], 0, v[132:133]
	s_waitcnt lgkmcnt(1)
	v_mov_b32_e32 v132, v206
	v_mov_b32_e32 v133, v207
	v_mov_b32_e32 v134, v208
	v_mov_b32_e32 v135, v209
	v_mov_b32_e32 v156, v133
	v_mov_b32_e32 v157, v134
	v_mov_b32_e32 v133, v135
.LBB0_574:
	s_or_b64 exec, exec, s[18:19]
	v_pk_add_f32 v[132:133], v[156:157], v[132:133]
	v_or_b32_e32 v158, 48, v154
	v_add_f32_e32 v131, v132, v133
	ds_bpermute_b32 v132, v176, v131
	v_mov_b32_e32 v134, 0
	v_mov_b32_e32 v135, 0
	s_waitcnt lgkmcnt(0)
	v_add_f32_e32 v173, v131, v132
	ds_bpermute_b32 v174, v168, v173
	v_mov_b32_e32 v131, 0
	s_and_saveexec_b64 s[18:19], s[44:45]
	s_cbranch_execz .LBB0_576
	v_ashrrev_i32_e32 v159, 31, v158
	v_lshlrev_b64 v[130:131], 6, v[158:159]
	v_lshl_add_u64 v[130:131], v[146:147], 0, v[130:131]
	s_waitcnt lgkmcnt(1)
	v_mov_b32_e32 v130, v210
	v_mov_b32_e32 v131, v211
	v_mov_b32_e32 v132, v212
	v_mov_b32_e32 v133, v213
	v_mov_b32_e32 v134, v131
	v_mov_b32_e32 v135, v132
	v_mov_b32_e32 v131, v133
.LBB0_576:
	s_or_b64 exec, exec, s[18:19]
	v_pk_add_f32 v[130:131], v[134:135], v[130:131]
	v_add_u32_e32 v156, 0x80, v154
	v_add_f32_e32 v130, v130, v131
	ds_bpermute_b32 v131, v176, v130
	v_mov_b32_e32 v132, 0
	v_mov_b32_e32 v164, 0
	v_mov_b32_e32 v165, 0
	v_mov_b32_e32 v133, 0
	s_waitcnt lgkmcnt(0)
	v_add_f32_e32 v171, v130, v131
	ds_bpermute_b32 v172, v168, v171
	v_mov_b32_e32 v130, 0
	s_and_saveexec_b64 s[18:19], s[44:45]
	s_cbranch_execz .LBB0_578
	v_ashrrev_i32_e32 v157, 31, v156
	v_lshlrev_b64 v[132:133], 6, v[156:157]
	v_lshl_add_u64 v[132:133], v[146:147], 0, v[132:133]
	s_waitcnt lgkmcnt(1)
	v_mov_b32_e32 v132, v214
	v_mov_b32_e32 v133, v215
	v_mov_b32_e32 v134, v216
	v_mov_b32_e32 v135, v217
	v_mov_b32_e32 v164, v133
	v_mov_b32_e32 v165, v134
	v_mov_b32_e32 v133, v135
.LBB0_578:
	s_or_b64 exec, exec, s[18:19]
	v_pk_add_f32 v[132:133], v[164:165], v[132:133]
	v_mov_b32_e32 v134, 0
	v_add_f32_e32 v131, v132, v133
	ds_bpermute_b32 v132, v176, v131
	v_mov_b32_e32 v135, 0
	s_waitcnt lgkmcnt(0)
	v_add_f32_e32 v169, v131, v132
	ds_bpermute_b32 v170, v168, v169
	v_mov_b32_e32 v131, 0
	s_and_saveexec_b64 s[18:19], s[44:45]
	s_cbranch_execz .LBB0_580
	v_lshlrev_b64 v[130:131], 6, v[154:155]
	v_lshl_add_u64 v[130:131], v[146:147], 0, v[130:131]
	v_add_co_u32_e32 v130, vcc, 0x2000, v130
	s_nop 1
	v_addc_co_u32_e32 v131, vcc, 0, v131, vcc
	s_waitcnt lgkmcnt(1)
	v_mov_b32_e32 v130, v218
	v_mov_b32_e32 v131, v219
	v_mov_b32_e32 v132, v220
	v_mov_b32_e32 v133, v221
	v_mov_b32_e32 v134, v131
	v_mov_b32_e32 v135, v132
	v_mov_b32_e32 v131, v133
.LBB0_580:
	s_or_b64 exec, exec, s[18:19]
	v_pk_add_f32 v[130:131], v[134:135], v[130:131]
	v_mov_b32_e32 v132, 0
	v_add_f32_e32 v130, v130, v131
	ds_bpermute_b32 v131, v176, v130
	v_mov_b32_e32 v164, 0
	v_mov_b32_e32 v165, 0
	v_mov_b32_e32 v133, 0
	s_waitcnt lgkmcnt(0)
	v_add_f32_e32 v161, v130, v131
	ds_bpermute_b32 v163, v168, v161
	v_mov_b32_e32 v130, 0
	s_and_saveexec_b64 s[18:19], s[44:45]
	s_cbranch_execz .LBB0_582
	v_lshlrev_b64 v[132:133], 6, v[154:155]
	v_lshl_add_u64 v[132:133], v[146:147], 0, v[132:133]
	v_add_co_u32_e32 v132, vcc, 0x2000, v132
	s_nop 1
	v_addc_co_u32_e32 v133, vcc, 0, v133, vcc
	s_waitcnt lgkmcnt(1)
	v_mov_b32_e32 v132, v226
	v_mov_b32_e32 v133, v227
	v_mov_b32_e32 v134, v228
	v_mov_b32_e32 v135, v229
	v_mov_b32_e32 v164, v133
	v_mov_b32_e32 v165, v134
	v_mov_b32_e32 v133, v135
.LBB0_582:
	s_or_b64 exec, exec, s[18:19]
	v_pk_add_f32 v[132:133], v[164:165], v[132:133]
	v_mov_b32_e32 v134, 0
	v_add_f32_e32 v131, v132, v133
	ds_bpermute_b32 v132, v176, v131
	v_mov_b32_e32 v135, 0
	s_waitcnt lgkmcnt(0)
	v_add_f32_e32 v157, v131, v132
	ds_bpermute_b32 v159, v168, v157
	v_mov_b32_e32 v131, 0
	s_and_saveexec_b64 s[18:19], s[44:45]
	s_cbranch_execz .LBB0_584
	v_lshlrev_b64 v[130:131], 6, v[154:155]
	v_lshl_add_u64 v[130:131], v[146:147], 0, v[130:131]
	v_add_co_u32_e32 v130, vcc, 0x2000, v130
	s_nop 1
	v_addc_co_u32_e32 v131, vcc, 0, v131, vcc
	s_waitcnt lgkmcnt(1)
	v_mov_b32_e32 v130, v230
	v_mov_b32_e32 v131, v231
	v_mov_b32_e32 v132, v232
	v_mov_b32_e32 v133, v233
	v_mov_b32_e32 v134, v131
	v_mov_b32_e32 v135, v132
	v_mov_b32_e32 v131, v133

; #define PG8_STAGE(bufoff, gbase, voff) do { _Pragma("unroll") for (int _i = 0; _i < 2; ++_i) \
;         __builtin_amdgcn_global_load_lds((const unsigned*)((const char*)(gbase) + (voff)[_i]), (LAS unsigned*)(lds + (bufoff) + ldsw + _i * 8192), 16, 0, 0); } while (0)
; #define PG8_LDA(dst, b, h) do { _Pragma("unroll") for (int m = 0; m < 4; ++m) _Pragma("unroll") for (int k = 0; k < 2; ++k) dst[m][k] = *(const LAS bf16x8*)(lds + PG8_SA(b, h) + aoff + m * 2048 + k * 1024); } while (0)
; #define PG8_BAR __builtin_amdgcn_s_barrier()
; template <class Epi>
; __device__ __forceinline__ void gemm_phase(LAS unsigned char* lds, int wave_s, const Gemm g, const StaticOrder S, const Epi E) {
;     ...
;         for (int t = 0; t < nt; t += 2) {
;             const bool last = (t == nt - 2);
;             const char* a1 = cA + (size_t)(t + 1) * kstep;
;             const char* a2 = last ? nA : cA + (size_t)(t + 2) * kstep; const char* b2 = last ? nB : cB + (size_t)(t + 2) * kstep;
;             const char* a3 = a2 + kstep; const char* b3 = b2 + kstep;
;             PG8_LDB(B0, 0, 0); PG8_LDB(B1, 0, 1); PG8_SCHED; PG8_LDA(At, 0, 0); PG8_STAGE(PG8_SA(1, 1), a1 + hstepA, voffA);
;             PG8_WAIT_V(8); PG8_WAIT_L(0); PG8_BAR; PG8_MMA(0, 0, At, B0); PG8_MMA(0, 1, At, B1); PG8_BAR; PG8_SCHED;
;             PG8_LDA(At, 0, 1); PG8_STAGE(PG8_SB(0, 0), b2, voffB); PG8_STAGE(PG8_SB(0, 1), b2 + hstepB, voffB); PG8_STAGE(PG8_SA(0, 0), a2, voffA);
;             PG8_WAIT_V(8); PG8_WAIT_L(0); PG8_BAR; PG8_MMA(1, 0, At, B0); PG8_MMA(1, 1, At, B1); PG8_BAR; PG8_SCHED;
;             PG8_LDB(B0, 1, 0); PG8_LDB(B1, 1, 1); PG8_SCHED; PG8_LDA(At, 1, 0); PG8_STAGE(PG8_SA(0, 1), a2 + hstepA, voffA);
;             PG8_WAIT_V(8); PG8_WAIT_L(0); PG8_BAR; PG8_MMA(0, 0, At, B0); PG8_MMA(0, 1, At, B1); PG8_BAR; PG8_SCHED;
;             PG8_LDA(At, 1, 1); PG8_STAGE(PG8_SB(1, 0), b3, voffB); PG8_STAGE(PG8_SB(1, 1), b3 + hstepB, voffB); PG8_STAGE(PG8_SA(1, 0), a3, voffA);
;             PG8_WAIT_V(8); PG8_WAIT_L(0); PG8_BAR; PG8_MMA(1, 0, At, B0); PG8_MMA(1, 1, At, B1); PG8_BAR; PG8_SCHED;
; __global__ void __launch_bounds__(512) fwd_megakernel(Args a) {
;     ...
;             { pg8::Gemm g{ACT + C_CKV, Wb + W_UKV, MC, KVAW, 256, INP}; pg8::StaticOrder S; S.init(MC, KVAW, G, bx);
;               pg8::EpiGen E{KVA, KVAW, PKV, 1.f / 256.f, 0, nullptr, nullptr, rope, 8, 2}; pg8::gemm_phase(lds, wave_s, g, S, E); }
.LBB0_635:
	s_add_u32 s12, s24, s11
	s_addc_u32 s13, s25, 0
	s_add_u32 s28, s12, 0x100
	s_addc_u32 s29, s13, 0
	s_and_b64 s[6:7], s[26:27], exec
	s_cselect_b32 s31, s19, s29
	s_cselect_b32 s30, s18, s28
	s_add_u32 s6, s22, s11
	s_addc_u32 s7, s23, 0
	s_add_u32 s11, s6, 0x100
	s_addc_u32 s28, s7, 0
	s_add_i32 s43, 0, 0x10000
	s_and_b64 s[6:7], s[26:27], exec
	s_cselect_b32 s35, s17, s28
	s_cselect_b32 s34, s10, s11
	s_add_i32 s6, 0, 0x14000
	s_add_u32 s48, s12, 0x210080
	s_addc_u32 s49, s13, 0
	s_add_i32 s12, s43, s37
	s_add_i32 m0, s95, 0xc000
	s_add_i32 s40, s95, 0xe000
	s_add_i32 s59, s12, 0x2000
	v_add_u32_e32 v134, s43, v161
	s_add_u32 s38, s34, 0x10000
	ds_read_b128 v[130:133], v134
	ds_read_b128 v[146:149], v134 offset:1024
	ds_read_b128 v[150:153], v134 offset:2048
	ds_read_b128 v[154:157], v134 offset:3072
	v_add_u32_e32 v134, s6, v161
	s_addc_u32 s39, s35, 0
	s_add_i32 s13, s6, s37
	ds_read_b128 v[164:167], v134
	ds_read_b128 v[168:171], v134 offset:1024
	ds_read_b128 v[172:175], v134 offset:2048
	ds_read_b128 v[176:179], v134 offset:3072
	s_add_i32 s42, s13, 0x2000
	s_add_i32 vcc_lo, 0, 0x18000
	s_add_i32 vcc_hi, 0, 0x1c000
	s_add_u32 s28, s30, 0x210000
	s_addc_u32 s29, s31, 0
	s_add_i32 s11, vcc_lo, s37
	s_add_i32 s58, s11, 0x2000
	s_add_u32 s26, s34, 0x10080
	s_addc_u32 s27, s35, 0
	s_add_i32 s7, vcc_hi, s37
	s_add_i32 s6, s7, 0x2000
	v_lshl_add_u64 v[134:135], s[48:49], 0, v[142:143]
	ds_read_b128 v[180:183], v163
	ds_read_b128 v[184:187], v163 offset:1024
	ds_read_b128 v[188:191], v163 offset:2048
	ds_read_b128 v[192:195], v163 offset:3072
	ds_read_b128 v[206:209], v163 offset:4096
	ds_read_b128 v[210:213], v163 offset:5120
	ds_read_b128 v[214:217], v163 offset:6144
	ds_read_b128 v[218:221], v163 offset:7168
	global_load_lds_dwordx4 v[134:135], off
	v_lshl_add_u64 v[134:135], s[48:49], 0, v[138:139]
	s_mov_b32 m0, s40
	s_nop 0
	global_load_lds_dwordx4 v[134:135], off
	s_waitcnt vmcnt(8)
	s_waitcnt lgkmcnt(0)
	s_barrier
	s_cmp_lg_u64 s[0:1], 0
	s_cbranch_scc0 .Lsq_ukv_skip
	v_readlane_b32 s100, v144, 0
	v_readlane_b32 s101, v145, 0
	s_lshl_b32 s98, s53, 13
	s_lshl_b32 s99, s92, 4
	s_add_u32 s98, s98, s99
	s_add_u32 s100, s100, s98
	s_addc_u32 s101, s101, 0
	s_add_i32 m0, s99, 0x24000
	v_lshlrev_b32_e32 v243, 4, v241
	s_nop 1
	global_load_lds_dwordx4 v243, s[100:101]
.Lsq_ukv_skip:
	s_setprio 1
	s_waitcnt lgkmcnt(0)
	v_mfma_f32_16x16x32_bf16 v[126:129], v[130:133], v[180:183], v[126:129]
	v_mfma_f32_16x16x32_bf16 v[122:125], v[150:153], v[180:183], v[122:125]
	v_mfma_f32_16x16x32_bf16 v[118:121], v[130:133], v[188:191], v[118:121]
	v_mfma_f32_16x16x32_bf16 v[114:117], v[150:153], v[188:191], v[114:117]
	v_mfma_f32_16x16x32_bf16 v[110:113], v[130:133], v[206:209], v[110:113]
	v_mfma_f32_16x16x32_bf16 v[106:109], v[150:153], v[206:209], v[106:109]
	v_mfma_f32_16x16x32_bf16 v[102:105], v[130:133], v[214:217], v[102:105]
	v_mfma_f32_16x16x32_bf16 v[98:101], v[150:153], v[214:217], v[98:101]
	v_mfma_f32_16x16x32_bf16 v[126:129], v[146:149], v[184:187], v[126:129]
	v_mfma_f32_16x16x32_bf16 v[122:125], v[154:157], v[184:187], v[122:125]
	v_mfma_f32_16x16x32_bf16 v[118:121], v[146:149], v[192:195], v[118:121]
	v_mfma_f32_16x16x32_bf16 v[114:117], v[154:157], v[192:195], v[114:117]
	v_mfma_f32_16x16x32_bf16 v[110:113], v[146:149], v[210:213], v[110:113]
	v_mfma_f32_16x16x32_bf16 v[106:109], v[154:157], v[210:213], v[106:109]
	v_mfma_f32_16x16x32_bf16 v[102:105], v[146:149], v[218:221], v[102:105]
	v_mfma_f32_16x16x32_bf16 v[98:101], v[154:157], v[218:221], v[98:101]
	s_setprio 0
	s_setprio 1
	v_mfma_f32_16x16x32_bf16 v[78:81], v[164:167], v[180:183], v[78:81]
	v_mfma_f32_16x16x32_bf16 v[70:73], v[172:175], v[180:183], v[70:73]
	v_mfma_f32_16x16x32_bf16 v[62:65], v[164:167], v[188:191], v[62:65]
	v_mfma_f32_16x16x32_bf16 v[58:61], v[172:175], v[188:191], v[58:61]
	v_mfma_f32_16x16x32_bf16 v[46:49], v[164:167], v[206:209], v[46:49]
	v_mfma_f32_16x16x32_bf16 v[42:45], v[172:175], v[206:209], v[42:45]
	v_mfma_f32_16x16x32_bf16 v[38:41], v[164:167], v[214:217], v[38:41]
	v_mfma_f32_16x16x32_bf16 v[34:37], v[172:175], v[214:217], v[34:37]
	v_mfma_f32_16x16x32_bf16 v[78:81], v[168:171], v[184:187], v[78:81]
	v_mfma_f32_16x16x32_bf16 v[70:73], v[176:179], v[184:187], v[70:73]
	v_mfma_f32_16x16x32_bf16 v[62:65], v[168:171], v[192:195], v[62:65]
	v_mfma_f32_16x16x32_bf16 v[58:61], v[176:179], v[192:195], v[58:61]
	v_mfma_f32_16x16x32_bf16 v[46:49], v[168:171], v[210:213], v[46:49]
	v_mfma_f32_16x16x32_bf16 v[42:45], v[176:179], v[210:213], v[42:45]
	v_mfma_f32_16x16x32_bf16 v[38:41], v[168:171], v[218:221], v[38:41]
	v_mfma_f32_16x16x32_bf16 v[34:37], v[176:179], v[218:221], v[34:37]
	s_setprio 0
	s_barrier
	s_mov_b32 m0, s12
	v_lshl_add_u64 v[134:135], s[34:35], 0, v[140:141]
	ds_read_b128 v[180:183], v163 offset:16384
	ds_read_b128 v[184:187], v163 offset:17408
	ds_read_b128 v[188:191], v163 offset:18432
	ds_read_b128 v[192:195], v163 offset:19456
	ds_read_b128 v[206:209], v163 offset:20480
	ds_read_b128 v[210:213], v163 offset:21504
	ds_read_b128 v[214:217], v163 offset:22528
	ds_read_b128 v[218:221], v163 offset:23552
	global_load_lds_dwordx4 v[134:135], off
	v_lshl_add_u64 v[196:197], s[34:35], 0, v[136:137]
	s_mov_b32 m0, s59
	v_lshl_add_u64 v[198:199], s[38:39], 0, v[140:141]
	global_load_lds_dwordx4 v[196:197], off
	s_mov_b32 m0, s13
	v_lshl_add_u64 v[200:201], s[30:31], 0, v[138:139]
	global_load_lds_dwordx4 v[198:199], off
	v_lshl_add_u64 v[198:199], s[38:39], 0, v[136:137]
	s_mov_b32 m0, s42
	s_nop 0
	global_load_lds_dwordx4 v[198:199], off
	v_lshl_add_u64 v[198:199], s[30:31], 0, v[142:143]
	s_mov_b32 m0, s95
	s_nop 0
	global_load_lds_dwordx4 v[198:199], off
	s_mov_b32 m0, s50
	s_nop 0
	global_load_lds_dwordx4 v[200:201], off
	s_waitcnt vmcnt(8)
	s_waitcnt lgkmcnt(0)
	s_barrier
; #define PG8_STAGE(bufoff, gbase, voff) do { _Pragma("unroll") for (int _i = 0; _i < 2; ++_i) \
;         __builtin_amdgcn_global_load_lds((const unsigned*)((const char*)(gbase) + (voff)[_i]), (LAS unsigned*)(lds + (bufoff) + ldsw + _i * 8192), 16, 0, 0); } while (0)
; #define PG8_LDA(dst, b, h) do { _Pragma("unroll") for (int m = 0; m < 4; ++m) _Pragma("unroll") for (int k = 0; k < 2; ++k) dst[m][k] = *(const LAS bf16x8*)(lds + PG8_SA(b, h) + aoff + m * 2048 + k * 1024); } while (0)
; #define PG8_LDB(dst, b, h) do { _Pragma("unroll") for (int n = 0; n < 2; ++n) _Pragma("unroll") for (int k = 0; k < 2; ++k) dst[n][k] = *(const LAS bf16x8*)(lds + PG8_SB(b, h) + boff + n * 2048 + k * 1024); } while (0)
; #define PG8_MMA(ai, bj, At, Bt) do { __builtin_amdgcn_s_setprio(1); _Pragma("unroll") for (int m = 0; m < 4; ++m) _Pragma("unroll") for (int n = 0; n < 2; ++n) _Pragma("unroll") for (int k = 0; k < 2; ++k) \
;         acc[ai][bj][m][n] = __builtin_amdgcn_mfma_f32_16x16x32_bf16(Bt[n][k], At[m][k], acc[ai][bj][m][n], 0, 0, 0); __builtin_amdgcn_s_setprio(0); } while (0)
; #define PG8_WAIT_V(n) asm volatile("s_waitcnt vmcnt(" #n ")" ::: "memory")
; #define PG8_WAIT_L(n) asm volatile("s_waitcnt lgkmcnt(" #n ")" ::: "memory")
; #define PG8_BAR __builtin_amdgcn_s_barrier()
; #define PG8_SCHED __builtin_amdgcn_sched_barrier(0)
; template <class Epi>
; __device__ __forceinline__ void gemm_phase(LAS unsigned char* lds, int wave_s, const Gemm g, const StaticOrder S, const Epi E) {
;     ...
;             PG8_WAIT_V(8); PG8_WAIT_L(0); PG8_BAR; PG8_MMA(0, 0, At, B0); PG8_MMA(0, 1, At, B1); PG8_BAR; PG8_SCHED;
;             PG8_LDA(At, 0, 1); PG8_STAGE(PG8_SB(0, 0), b2, voffB); PG8_STAGE(PG8_SB(0, 1), b2 + hstepB, voffB); PG8_STAGE(PG8_SA(0, 0), a2, voffA);
;             PG8_WAIT_V(8); PG8_WAIT_L(0); PG8_BAR; PG8_MMA(1, 0, At, B0); PG8_MMA(1, 1, At, B1); PG8_BAR; PG8_SCHED;
;             PG8_LDB(B0, 1, 0); PG8_LDB(B1, 1, 1); PG8_SCHED; PG8_LDA(At, 1, 0); PG8_STAGE(PG8_SA(0, 1), a2 + hstepA, voffA);
;             PG8_WAIT_V(8); PG8_WAIT_L(0); PG8_BAR; PG8_MMA(0, 0, At, B0); PG8_MMA(0, 1, At, B1); PG8_BAR; PG8_SCHED;
	s_setprio 1
	s_waitcnt lgkmcnt(0)
	v_mfma_f32_16x16x32_bf16 v[94:97], v[130:133], v[180:183], v[94:97]
	v_mfma_f32_16x16x32_bf16 v[90:93], v[150:153], v[180:183], v[90:93]
	v_mfma_f32_16x16x32_bf16 v[86:89], v[130:133], v[188:191], v[86:89]
	v_mfma_f32_16x16x32_bf16 v[82:85], v[150:153], v[188:191], v[82:85]
	v_mfma_f32_16x16x32_bf16 v[74:77], v[130:133], v[206:209], v[74:77]
	v_mfma_f32_16x16x32_bf16 v[66:69], v[150:153], v[206:209], v[66:69]
	v_mfma_f32_16x16x32_bf16 v[54:57], v[130:133], v[214:217], v[54:57]
	v_mfma_f32_16x16x32_bf16 v[50:53], v[150:153], v[214:217], v[50:53]
	v_mfma_f32_16x16x32_bf16 v[94:97], v[146:149], v[184:187], v[94:97]
	v_mfma_f32_16x16x32_bf16 v[90:93], v[154:157], v[184:187], v[90:93]
	v_mfma_f32_16x16x32_bf16 v[86:89], v[146:149], v[192:195], v[86:89]
	v_mfma_f32_16x16x32_bf16 v[82:85], v[154:157], v[192:195], v[82:85]
	v_mfma_f32_16x16x32_bf16 v[74:77], v[146:149], v[210:213], v[74:77]
	v_mfma_f32_16x16x32_bf16 v[66:69], v[154:157], v[210:213], v[66:69]
	v_mfma_f32_16x16x32_bf16 v[54:57], v[146:149], v[218:221], v[54:57]
	v_mfma_f32_16x16x32_bf16 v[50:53], v[154:157], v[218:221], v[50:53]
	s_setprio 0
	s_setprio 1
	v_mfma_f32_16x16x32_bf16 v[30:33], v[164:167], v[180:183], v[30:33]
	v_mfma_f32_16x16x32_bf16 v[26:29], v[172:175], v[180:183], v[26:29]
	v_mfma_f32_16x16x32_bf16 v[22:25], v[164:167], v[188:191], v[22:25]
	v_mfma_f32_16x16x32_bf16 v[18:21], v[172:175], v[188:191], v[18:21]
	v_mfma_f32_16x16x32_bf16 v[14:17], v[164:167], v[206:209], v[14:17]
	v_mfma_f32_16x16x32_bf16 v[10:13], v[172:175], v[206:209], v[10:13]
	v_mfma_f32_16x16x32_bf16 v[6:9], v[164:167], v[214:217], v[6:9]
	v_mfma_f32_16x16x32_bf16 v[2:5], v[172:175], v[214:217], v[2:5]
	v_mfma_f32_16x16x32_bf16 v[30:33], v[168:171], v[184:187], v[30:33]
	v_mfma_f32_16x16x32_bf16 v[26:29], v[176:179], v[184:187], v[26:29]
	v_mfma_f32_16x16x32_bf16 v[22:25], v[168:171], v[192:195], v[22:25]
	v_mfma_f32_16x16x32_bf16 v[18:21], v[176:179], v[192:195], v[18:21]
	v_mfma_f32_16x16x32_bf16 v[14:17], v[168:171], v[210:213], v[14:17]
	v_mfma_f32_16x16x32_bf16 v[10:13], v[176:179], v[210:213], v[10:13]
	v_mfma_f32_16x16x32_bf16 v[6:9], v[168:171], v[218:221], v[6:9]
	v_mfma_f32_16x16x32_bf16 v[2:5], v[176:179], v[218:221], v[2:5]
	s_setprio 0
	s_barrier
	v_add_u32_e32 v154, vcc_lo, v161
	v_add_u32_e32 v158, vcc_hi, v161
	ds_read_b128 v[130:133], v154
	ds_read_b128 v[146:149], v154 offset:1024
	ds_read_b128 v[150:153], v154 offset:2048
	ds_read_b128 v[154:157], v154 offset:3072
	ds_read_b128 v[164:167], v158
	ds_read_b128 v[168:171], v158 offset:1024
	ds_read_b128 v[172:175], v158 offset:2048
	ds_read_b128 v[176:179], v158 offset:3072
	s_mov_b32 m0, s51
	v_lshl_add_u64 v[202:203], s[28:29], 0, v[142:143]
	ds_read_b128 v[180:183], v163 offset:32768
	ds_read_b128 v[184:187], v163 offset:33792
	ds_read_b128 v[188:191], v163 offset:34816
	ds_read_b128 v[192:195], v163 offset:35840
	ds_read_b128 v[206:209], v163 offset:36864
	ds_read_b128 v[210:213], v163 offset:37888
	ds_read_b128 v[214:217], v163 offset:38912
	ds_read_b128 v[218:221], v163 offset:39936
	global_load_lds_dwordx4 v[202:203], off
	v_lshl_add_u64 v[202:203], s[28:29], 0, v[138:139]
	s_mov_b32 m0, s54
	s_nop 0
	global_load_lds_dwordx4 v[202:203], off
	s_waitcnt vmcnt(8)
	s_waitcnt lgkmcnt(0)
	s_barrier
	s_setprio 1
	s_waitcnt lgkmcnt(0)
	v_mfma_f32_16x16x32_bf16 v[126:129], v[130:133], v[180:183], v[126:129]
	v_mfma_f32_16x16x32_bf16 v[122:125], v[150:153], v[180:183], v[122:125]
	v_mfma_f32_16x16x32_bf16 v[118:121], v[130:133], v[188:191], v[118:121]
	v_mfma_f32_16x16x32_bf16 v[114:117], v[150:153], v[188:191], v[114:117]
	v_mfma_f32_16x16x32_bf16 v[110:113], v[130:133], v[206:209], v[110:113]
	v_mfma_f32_16x16x32_bf16 v[106:109], v[150:153], v[206:209], v[106:109]
	v_mfma_f32_16x16x32_bf16 v[102:105], v[130:133], v[214:217], v[102:105]
	v_mfma_f32_16x16x32_bf16 v[98:101], v[150:153], v[214:217], v[98:101]
	v_mfma_f32_16x16x32_bf16 v[126:129], v[146:149], v[184:187], v[126:129]
	v_mfma_f32_16x16x32_bf16 v[122:125], v[154:157], v[184:187], v[122:125]
	v_mfma_f32_16x16x32_bf16 v[118:121], v[146:149], v[192:195], v[118:121]
	v_mfma_f32_16x16x32_bf16 v[114:117], v[154:157], v[192:195], v[114:117]
	v_mfma_f32_16x16x32_bf16 v[110:113], v[146:149], v[210:213], v[110:113]
	v_mfma_f32_16x16x32_bf16 v[106:109], v[154:157], v[210:213], v[106:109]
	v_mfma_f32_16x16x32_bf16 v[102:105], v[146:149], v[218:221], v[102:105]
	v_mfma_f32_16x16x32_bf16 v[98:101], v[154:157], v[218:221], v[98:101]
	s_setprio 0
	s_setprio 1
	v_mfma_f32_16x16x32_bf16 v[78:81], v[164:167], v[180:183], v[78:81]
	v_mfma_f32_16x16x32_bf16 v[70:73], v[172:175], v[180:183], v[70:73]
	v_mfma_f32_16x16x32_bf16 v[62:65], v[164:167], v[188:191], v[62:65]
	v_mfma_f32_16x16x32_bf16 v[58:61], v[172:175], v[188:191], v[58:61]
	v_mfma_f32_16x16x32_bf16 v[46:49], v[164:167], v[206:209], v[46:49]
	v_mfma_f32_16x16x32_bf16 v[42:45], v[172:175], v[206:209], v[42:45]
	v_mfma_f32_16x16x32_bf16 v[38:41], v[164:167], v[214:217], v[38:41]
	v_mfma_f32_16x16x32_bf16 v[34:37], v[172:175], v[214:217], v[34:37]
	v_mfma_f32_16x16x32_bf16 v[78:81], v[168:171], v[184:187], v[78:81]
	v_mfma_f32_16x16x32_bf16 v[70:73], v[176:179], v[184:187], v[70:73]
	v_mfma_f32_16x16x32_bf16 v[62:65], v[168:171], v[192:195], v[62:65]
	v_mfma_f32_16x16x32_bf16 v[58:61], v[176:179], v[192:195], v[58:61]
	v_mfma_f32_16x16x32_bf16 v[46:49], v[168:171], v[210:213], v[46:49]
	v_mfma_f32_16x16x32_bf16 v[42:45], v[176:179], v[210:213], v[42:45]
	v_mfma_f32_16x16x32_bf16 v[38:41], v[168:171], v[218:221], v[38:41]
	v_mfma_f32_16x16x32_bf16 v[34:37], v[176:179], v[218:221], v[34:37]
	s_setprio 0
	s_barrier
; #define PG8_STAGE(bufoff, gbase, voff) do { _Pragma("unroll") for (int _i = 0; _i < 2; ++_i) \
;         __builtin_amdgcn_global_load_lds((const unsigned*)((const char*)(gbase) + (voff)[_i]), (LAS unsigned*)(lds + (bufoff) + ldsw + _i * 8192), 16, 0, 0); } while (0)
; #define PG8_LDA(dst, b, h) do { _Pragma("unroll") for (int m = 0; m < 4; ++m) _Pragma("unroll") for (int k = 0; k < 2; ++k) dst[m][k] = *(const LAS bf16x8*)(lds + PG8_SA(b, h) + aoff + m * 2048 + k * 1024); } while (0)
; #define PG8_MMA(ai, bj, At, Bt) do { __builtin_amdgcn_s_setprio(1); _Pragma("unroll") for (int m = 0; m < 4; ++m) _Pragma("unroll") for (int n = 0; n < 2; ++n) _Pragma("unroll") for (int k = 0; k < 2; ++k) \
;         acc[ai][bj][m][n] = __builtin_amdgcn_mfma_f32_16x16x32_bf16(Bt[n][k], At[m][k], acc[ai][bj][m][n], 0, 0, 0); __builtin_amdgcn_s_setprio(0); } while (0)
; #define PG8_WAIT_V(n) asm volatile("s_waitcnt vmcnt(" #n ")" ::: "memory")
; #define PG8_WAIT_L(n) asm volatile("s_waitcnt lgkmcnt(" #n ")" ::: "memory")
; #define PG8_BAR __builtin_amdgcn_s_barrier()
; #define PG8_SCHED __builtin_amdgcn_sched_barrier(0)
; __device__ __forceinline__ float row_ssq(const float* part, int pitch, int n4, int row, int fq) {
;     f32x4 v = (f32x4){0.f, 0.f, 0.f, 0.f};
;     if (fq < n4) v = *(const f32x4*)(part + (size_t)row * pitch + 4 * fq);
;     float s = (v[0] + v[1]) + (v[2] + v[3]);
;     s += __shfl_xor(s, 16); s += __shfl_xor(s, 32);
;     return s;
; template <class Epi>
; __device__ __forceinline__ void gemm_phase(LAS unsigned char* lds, int wave_s, const Gemm g, const StaticOrder S, const Epi E) {
;     ...
;             PG8_LDA(At, 1, 1); PG8_STAGE(PG8_SB(1, 0), b3, voffB); PG8_STAGE(PG8_SB(1, 1), b3 + hstepB, voffB); PG8_STAGE(PG8_SA(1, 0), a3, voffA);
;             PG8_WAIT_V(8); PG8_WAIT_L(0); PG8_BAR; PG8_MMA(1, 0, At, B0); PG8_MMA(1, 1, At, B1); PG8_BAR; PG8_SCHED;
;         }
;         if (wr == 0) PG8_BAR;
	s_mov_b32 m0, s11
	v_lshl_add_u64 v[134:135], v[134:135], 0, s[8:9]
	ds_read_b128 v[180:183], v163 offset:49152
	ds_read_b128 v[184:187], v163 offset:50176
	ds_read_b128 v[188:191], v163 offset:51200
	ds_read_b128 v[192:195], v163 offset:52224
	ds_read_b128 v[206:209], v163 offset:53248
	ds_read_b128 v[210:213], v163 offset:54272
	ds_read_b128 v[214:217], v163 offset:55296
	ds_read_b128 v[218:221], v163 offset:56320
	global_load_lds_dwordx4 v[134:135], off
	v_lshl_add_u64 v[134:135], v[196:197], 0, s[8:9]
	s_mov_b32 m0, s58
	s_nop 0
	global_load_lds_dwordx4 v[134:135], off
	v_lshl_add_u64 v[134:135], s[26:27], 0, v[140:141]
	s_mov_b32 m0, s7
	s_nop 0
	global_load_lds_dwordx4 v[134:135], off
	v_lshl_add_u64 v[134:135], s[26:27], 0, v[136:137]
	s_mov_b32 m0, s6
	s_nop 0
	global_load_lds_dwordx4 v[134:135], off
	v_lshl_add_u64 v[134:135], v[198:199], 0, s[8:9]
	s_mov_b32 m0, s55
	s_nop 0
	global_load_lds_dwordx4 v[134:135], off
	v_lshl_add_u64 v[134:135], v[200:201], 0, s[8:9]
	s_mov_b32 m0, s56
	s_nop 0
	global_load_lds_dwordx4 v[134:135], off
	s_waitcnt vmcnt(8)
	s_waitcnt lgkmcnt(0)
	s_barrier
	s_setprio 1
	s_waitcnt lgkmcnt(0)
	v_mfma_f32_16x16x32_bf16 v[94:97], v[130:133], v[180:183], v[94:97]
	v_mfma_f32_16x16x32_bf16 v[90:93], v[150:153], v[180:183], v[90:93]
	v_mfma_f32_16x16x32_bf16 v[86:89], v[130:133], v[188:191], v[86:89]
	v_mfma_f32_16x16x32_bf16 v[82:85], v[150:153], v[188:191], v[82:85]
	v_mfma_f32_16x16x32_bf16 v[74:77], v[130:133], v[206:209], v[74:77]
	v_mfma_f32_16x16x32_bf16 v[66:69], v[150:153], v[206:209], v[66:69]
	v_mfma_f32_16x16x32_bf16 v[54:57], v[130:133], v[214:217], v[54:57]
	v_mfma_f32_16x16x32_bf16 v[50:53], v[150:153], v[214:217], v[50:53]
	v_mfma_f32_16x16x32_bf16 v[94:97], v[146:149], v[184:187], v[94:97]
	v_mfma_f32_16x16x32_bf16 v[90:93], v[154:157], v[184:187], v[90:93]
	v_mfma_f32_16x16x32_bf16 v[86:89], v[146:149], v[192:195], v[86:89]
	v_mfma_f32_16x16x32_bf16 v[82:85], v[154:157], v[192:195], v[82:85]
	v_mfma_f32_16x16x32_bf16 v[74:77], v[146:149], v[210:213], v[74:77]
	v_mfma_f32_16x16x32_bf16 v[66:69], v[154:157], v[210:213], v[66:69]
	v_mfma_f32_16x16x32_bf16 v[54:57], v[146:149], v[218:221], v[54:57]
	v_mfma_f32_16x16x32_bf16 v[50:53], v[154:157], v[218:221], v[50:53]
	s_setprio 0
	s_setprio 1
	v_mfma_f32_16x16x32_bf16 v[30:33], v[164:167], v[180:183], v[30:33]
	v_mfma_f32_16x16x32_bf16 v[26:29], v[172:175], v[180:183], v[26:29]
	v_mfma_f32_16x16x32_bf16 v[22:25], v[164:167], v[188:191], v[22:25]
	v_mfma_f32_16x16x32_bf16 v[18:21], v[172:175], v[188:191], v[18:21]
	v_mfma_f32_16x16x32_bf16 v[14:17], v[164:167], v[206:209], v[14:17]
	v_mfma_f32_16x16x32_bf16 v[10:13], v[172:175], v[206:209], v[10:13]
	v_mfma_f32_16x16x32_bf16 v[6:9], v[164:167], v[214:217], v[6:9]
	v_mfma_f32_16x16x32_bf16 v[2:5], v[172:175], v[214:217], v[2:5]
	v_mfma_f32_16x16x32_bf16 v[30:33], v[168:171], v[184:187], v[30:33]
	v_mfma_f32_16x16x32_bf16 v[26:29], v[176:179], v[184:187], v[26:29]
	v_mfma_f32_16x16x32_bf16 v[22:25], v[168:171], v[192:195], v[22:25]
	v_mfma_f32_16x16x32_bf16 v[18:21], v[176:179], v[192:195], v[18:21]
	v_mfma_f32_16x16x32_bf16 v[14:17], v[168:171], v[210:213], v[14:17]
	v_mfma_f32_16x16x32_bf16 v[10:13], v[176:179], v[210:213], v[10:13]
	v_mfma_f32_16x16x32_bf16 v[6:9], v[168:171], v[218:221], v[6:9]
	v_mfma_f32_16x16x32_bf16 v[2:5], v[176:179], v[218:221], v[2:5]
	s_setprio 0
	s_barrier
	s_movk_i32 s11, 0x100
	s_andn2_b64 vcc, exec, s[0:1]
	s_mov_b64 s[26:27], -1
	s_mov_b64 s[0:1], 0
	s_cbranch_vccz .LBB0_635
	s_and_b64 vcc, exec, s[14:15]
	s_cbranch_vccz .LBB0_638
	s_barrier
.LBB0_638:
	v_lshl_add_u32 v146, s53, 8, v159
	v_mov_b32_e32 v130, 0
	v_ashrrev_i32_e32 v147, 31, v146
	s_and_saveexec_b64 s[98:99], s[44:45]
	v_and_b32_e32 v234, 48, v241
	v_lshl_add_u32 v234, v159, 5, v234
	v_add_u32_e32 v234, 0x24000, v234
	ds_read_b128 v[194:197], v234
	ds_read_b128 v[198:201], v234 offset:512
	ds_read_b128 v[206:209], v234 offset:1024
	ds_read_b128 v[210:213], v234 offset:1536
	ds_read_b128 v[214:217], v234 offset:4096
	ds_read_b128 v[218:221], v234 offset:4608
	ds_read_b128 v[226:229], v234 offset:5120
	ds_read_b128 v[230:233], v234 offset:5632
	s_or_b64 exec, exec, s[98:99]
	v_mov_b32_e32 v132, 0
	v_mov_b32_e32 v148, 0
	v_mov_b32_e32 v149, 0
	v_mov_b32_e32 v133, 0
	s_and_saveexec_b64 s[0:1], s[44:45]
	s_cbranch_execz .LBB0_640
	v_lshlrev_b64 v[132:133], 5, v[146:147]
	v_lshl_add_u64 v[132:133], v[144:145], 0, v[132:133]
	s_waitcnt lgkmcnt(1)
	v_mov_b32_e32 v132, v194
	v_mov_b32_e32 v133, v195
	v_mov_b32_e32 v134, v196
	v_mov_b32_e32 v135, v197
	v_mov_b32_e32 v148, v133
	v_mov_b32_e32 v149, v134
	v_mov_b32_e32 v133, v135
.LBB0_640:
	s_or_b64 exec, exec, s[0:1]
	v_pk_add_f32 v[132:133], v[148:149], v[132:133]
	v_or_b32_e32 v148, 16, v146
	v_add_f32_e32 v131, v132, v133
	v_and_b32_e32 v133, 64, v241
	v_xor_b32_e32 v132, 16, v241
	v_add_u32_e32 v133, 64, v133
	v_cmp_lt_i32_e32 vcc, v132, v133
	v_ashrrev_i32_e32 v149, 31, v148
	v_mov_b32_e32 v134, 0
	v_cndmask_b32_e32 v132, v241, v132, vcc
	v_lshlrev_b32_e32 v167, 2, v132
	ds_bpermute_b32 v132, v167, v131
	v_mov_b32_e32 v135, 0
	s_waitcnt lgkmcnt(0)
	v_add_f32_e32 v166, v131, v132
	v_xor_b32_e32 v131, 32, v241
	v_cmp_lt_i32_e32 vcc, v131, v133
	s_nop 1
	v_cndmask_b32_e32 v131, v241, v131, vcc
	v_lshlrev_b32_e32 v165, 2, v131
	ds_bpermute_b32 v170, v165, v166
	v_mov_b32_e32 v131, 0
	s_and_saveexec_b64 s[0:1], s[44:45]
	s_cbranch_execz .LBB0_642
	v_lshlrev_b64 v[130:131], 5, v[148:149]
	v_lshl_add_u64 v[130:131], v[144:145], 0, v[130:131]
	s_waitcnt lgkmcnt(1)
	v_mov_b32_e32 v130, v198
	v_mov_b32_e32 v131, v199
	v_mov_b32_e32 v132, v200
	v_mov_b32_e32 v133, v201
	v_mov_b32_e32 v134, v131
	v_mov_b32_e32 v135, v132
	v_mov_b32_e32 v131, v133
; __device__ __forceinline__ float row_ssq(const float* part, int pitch, int n4, int row, int fq) {
;     f32x4 v = (f32x4){0.f, 0.f, 0.f, 0.f};
;     if (fq < n4) v = *(const f32x4*)(part + (size_t)row * pitch + 4 * fq);
;     float s = (v[0] + v[1]) + (v[2] + v[3]);
;     s += __shfl_xor(s, 16); s += __shfl_xor(s, 32);
;     return s;
;     __device__ __forceinline__ void operator()(const f32x4 (&acc)[2][2][4][2], const Unit& u, int wr, int wc, int fr, int fq) const {
;     ...
;         for (int ai = 0; ai < 2; ++ai)
; #pragma unroll
;             for (int m = 0; m < 4; ++m) rsv[ai][m] = ssq_in ? rsqrtf(row_ssq(ssq_in, in_pitch, in_n4, row0 + ai * HALF + m * 16, fq) * inv_k + EPS) : 1.f;
.LBB0_642:
	s_or_b64 exec, exec, s[0:1]
	v_pk_add_f32 v[130:131], v[134:135], v[130:131]
	v_or_b32_e32 v150, 32, v146
	v_add_f32_e32 v131, v130, v131
	ds_bpermute_b32 v132, v167, v131
	v_mov_b32_e32 v130, 0
	v_ashrrev_i32_e32 v151, 31, v150
	v_mov_b32_e32 v152, 0
	v_mov_b32_e32 v153, 0
	s_waitcnt lgkmcnt(0)
	v_add_f32_e32 v164, v131, v132
	ds_bpermute_b32 v171, v165, v164
	v_mov_b32_e32 v132, 0
	v_mov_b32_e32 v133, 0
	s_and_saveexec_b64 s[0:1], s[44:45]
	v_readlane_b32 s58, v254, 8
	v_readlane_b32 s30, v251, 4
	v_readlane_b32 s59, v254, 9
	v_readlane_b32 s31, v251, 5
	s_cbranch_execz .LBB0_644
	v_lshlrev_b64 v[132:133], 5, v[150:151]
	v_lshl_add_u64 v[132:133], v[144:145], 0, v[132:133]
	s_waitcnt lgkmcnt(1)
	v_mov_b32_e32 v132, v206
	v_mov_b32_e32 v133, v207
	v_mov_b32_e32 v134, v208
	v_mov_b32_e32 v135, v209
	v_mov_b32_e32 v152, v133
	v_mov_b32_e32 v153, v134
	v_mov_b32_e32 v133, v135
.LBB0_644:
	s_or_b64 exec, exec, s[0:1]
	v_pk_add_f32 v[132:133], v[152:153], v[132:133]
	v_or_b32_e32 v152, 48, v146
	v_add_f32_e32 v131, v132, v133
	ds_bpermute_b32 v132, v167, v131
	v_ashrrev_i32_e32 v153, 31, v152
	v_mov_b32_e32 v134, 0
	v_mov_b32_e32 v135, 0
	s_waitcnt lgkmcnt(0)
	v_add_f32_e32 v162, v131, v132
	ds_bpermute_b32 v172, v165, v162
	v_mov_b32_e32 v131, 0
	s_and_saveexec_b64 s[0:1], s[44:45]
	s_cbranch_execz .LBB0_646
	v_lshlrev_b64 v[130:131], 5, v[152:153]
	v_lshl_add_u64 v[130:131], v[144:145], 0, v[130:131]
	s_waitcnt lgkmcnt(1)
	v_mov_b32_e32 v130, v210
	v_mov_b32_e32 v131, v211
	v_mov_b32_e32 v132, v212
	v_mov_b32_e32 v133, v213
	v_mov_b32_e32 v134, v131
	v_mov_b32_e32 v135, v132
	v_mov_b32_e32 v131, v133
.LBB0_646:
	s_or_b64 exec, exec, s[0:1]
	v_pk_add_f32 v[130:131], v[134:135], v[130:131]
	v_add_u32_e32 v154, 0x80, v146
	v_add_f32_e32 v131, v130, v131
	ds_bpermute_b32 v132, v167, v131
	v_mov_b32_e32 v130, 0
	v_ashrrev_i32_e32 v155, 31, v154
	v_mov_b32_e32 v156, 0
	v_mov_b32_e32 v157, 0
	s_waitcnt lgkmcnt(0)
	v_add_f32_e32 v160, v131, v132
	ds_bpermute_b32 v173, v165, v160
	v_mov_b32_e32 v132, 0
	v_mov_b32_e32 v133, 0
	s_and_saveexec_b64 s[0:1], s[44:45]
	s_cbranch_execz .LBB0_648
	v_lshlrev_b64 v[132:133], 5, v[154:155]
	v_lshl_add_u64 v[132:133], v[144:145], 0, v[132:133]
	s_waitcnt lgkmcnt(1)
	v_mov_b32_e32 v132, v214
	v_mov_b32_e32 v133, v215
	v_mov_b32_e32 v134, v216
	v_mov_b32_e32 v135, v217
	v_mov_b32_e32 v156, v133
	v_mov_b32_e32 v157, v134
	v_mov_b32_e32 v133, v135
.LBB0_648:
	s_or_b64 exec, exec, s[0:1]
	v_pk_add_f32 v[132:133], v[156:157], v[132:133]
	v_mov_b32_e32 v134, 0
	v_add_f32_e32 v131, v132, v133
	ds_bpermute_b32 v132, v167, v131
	v_mov_b32_e32 v135, 0
	s_waitcnt lgkmcnt(0)
	v_add_f32_e32 v158, v131, v132
	ds_bpermute_b32 v174, v165, v158
	v_mov_b32_e32 v131, 0
	s_and_saveexec_b64 s[0:1], s[44:45]
	s_cbranch_execz .LBB0_650
	v_lshlrev_b64 v[130:131], 5, v[146:147]
	v_lshl_add_u64 v[130:131], v[144:145], 0, v[130:131]
	v_add_co_u32_e32 v130, vcc, 0x1000, v130
	s_nop 1
	v_addc_co_u32_e32 v131, vcc, 0, v131, vcc
	s_waitcnt lgkmcnt(1)
	v_mov_b32_e32 v130, v218
	v_mov_b32_e32 v131, v219
	v_mov_b32_e32 v132, v220
	v_mov_b32_e32 v133, v221
	v_mov_b32_e32 v134, v131
	v_mov_b32_e32 v135, v132
	v_mov_b32_e32 v131, v133
.LBB0_650:
	s_or_b64 exec, exec, s[0:1]
	v_pk_add_f32 v[130:131], v[134:135], v[130:131]
	v_mov_b32_e32 v132, 0
	v_add_f32_e32 v130, v130, v131
	ds_bpermute_b32 v131, v167, v130
	v_mov_b32_e32 v156, 0
	v_mov_b32_e32 v157, 0
	v_mov_b32_e32 v133, 0
	s_waitcnt lgkmcnt(0)
	v_add_f32_e32 v175, v130, v131
	ds_bpermute_b32 v176, v165, v175
	v_mov_b32_e32 v130, 0
	s_and_saveexec_b64 s[0:1], s[44:45]
	s_cbranch_execz .LBB0_652
	v_lshlrev_b64 v[132:133], 5, v[146:147]
	v_lshl_add_u64 v[132:133], v[144:145], 0, v[132:133]
	v_add_co_u32_e32 v132, vcc, 0x1000, v132
	s_nop 1
	v_addc_co_u32_e32 v133, vcc, 0, v133, vcc
	s_waitcnt lgkmcnt(1)
	v_mov_b32_e32 v132, v226
	v_mov_b32_e32 v133, v227
	v_mov_b32_e32 v134, v228
	v_mov_b32_e32 v135, v229
	v_mov_b32_e32 v156, v133
	v_mov_b32_e32 v157, v134
	v_mov_b32_e32 v133, v135
.LBB0_652:
	s_or_b64 exec, exec, s[0:1]
	v_pk_add_f32 v[132:133], v[156:157], v[132:133]
	v_add_u32_e32 v156, 0xb0, v146
	v_add_f32_e32 v131, v132, v133
	ds_bpermute_b32 v132, v167, v131
	v_ashrrev_i32_e32 v157, 31, v156
	v_mov_b32_e32 v168, 0
	v_mov_b32_e32 v169, 0
	s_waitcnt lgkmcnt(0)
	v_add_f32_e32 v134, v131, v132
	ds_bpermute_b32 v135, v165, v134
	v_mov_b32_e32 v131, 0
	s_and_saveexec_b64 s[0:1], s[44:45]
	s_cbranch_execz .LBB0_654
	v_lshlrev_b64 v[130:131], 5, v[156:157]
	v_lshl_add_u64 v[130:131], v[144:145], 0, v[130:131]
	s_waitcnt lgkmcnt(1)
	v_mov_b32_e32 v130, v230
	v_mov_b32_e32 v131, v231
	v_mov_b32_e32 v132, v232
	v_mov_b32_e32 v133, v233
	v_mov_b32_e32 v168, v131
	v_mov_b32_e32 v169, v132
	v_mov_b32_e32 v131, v133
